# grid barrier: non-leader workgroups issue the L1 invalidate right behind the arrival atomic (all other waves parked, polls use sc1) instead of after the release is observed
# speedup vs baseline: 1.0052x; 1.0052x over previous
; __device__ __forceinline__ unsigned xb_ld(unsigned* p)              { return __hip_atomic_load(p, __ATOMIC_RELAXED, __HIP_MEMORY_SCOPE_AGENT); }
; __device__ __forceinline__ unsigned xb_add(unsigned* p, unsigned v) { return __hip_atomic_fetch_add(p, v, __ATOMIC_RELAXED, __HIP_MEMORY_SCOPE_AGENT); }
; #define XB_SPIN(cond, bar) do { unsigned _sp = 0; while (cond) { __builtin_amdgcn_s_sleep(1); \
;     if ((++_sp & 255u) == 0u) { if (xb_ld(&(bar)[XB_TMO])) break; if (_sp > XB_SPIN_CAP) { atomicAdd(&(bar)[XB_TMO], 1u); break; } } } } while (0)
; __device__ __forceinline__ void xcd_barrier(const XcdBarrier& b) {
;     ...
;         const unsigned old = xb_add(&bar[XB_XSUB(b.x)], 1u);
;         const unsigned gen = old / nloc;
;         if (old + 1u == (gen + 1u) * nloc) {
;             __builtin_amdgcn_fence(__ATOMIC_RELEASE, "agent");
;             asm volatile("s_waitcnt vmcnt(0)" ::: "memory");
;             const unsigned og = xb_add(&bar[XB_TOP], 1u);
;             const unsigned tg = og / nx;
;             if (og + 1u == (tg + 1u) * nx) xb_add(&bar[XB_TOPGEN], 1u);
;             else XB_SPIN(xb_ld(&bar[XB_TOPGEN]) == tg, bar);
;             __builtin_amdgcn_fence(__ATOMIC_ACQUIRE, "agent");
;             xb_add(&bar[XB_XGEN(b.x)], 1u);
;             asm volatile("s_waitcnt vmcnt(0)" ::: "memory");
;         } else {
;             XB_SPIN(xb_ld(&bar[XB_XGEN(b.x)]) == gen, bar);
.LBB0_1050:
	v_readlane_b32 s0, v245, 47
	s_lshl_b32 s50, s0, 6
	s_lshl_b64 s[0:1], s[50:51], 2
	s_add_u32 s6, s60, s0
	s_addc_u32 s7, s61, s1
	global_atomic_add v3, v199, v200, s[6:7] offset:1024 sc0
	buffer_inv sc1
	v_cvt_f32_u32_e32 v1, v2
	v_sub_u32_e32 v4, 0, v2
	v_rcp_iflag_f32_e32 v1, v1
	s_nop 0
	v_mul_f32_e32 v1, 0x4f7ffffe, v1
	v_cvt_u32_f32_e32 v1, v1
	v_mul_lo_u32 v4, v4, v1
	v_mul_hi_u32 v4, v1, v4
	v_add_u32_e32 v1, v1, v4
	s_waitcnt vmcnt(0)
	v_mul_hi_u32 v1, v3, v1
	v_mul_lo_u32 v4, v1, v2
	v_sub_u32_e32 v4, v3, v4
	v_add_u32_e32 v5, 1, v1
	v_cmp_ge_u32_e32 vcc, v4, v2
	v_add_u32_e32 v3, 1, v3
	s_nop 0
	v_cndmask_b32_e32 v1, v1, v5, vcc
	v_sub_u32_e32 v5, v4, v2
	v_cndmask_b32_e32 v4, v4, v5, vcc
	v_add_u32_e32 v5, 1, v1
	v_cmp_ge_u32_e32 vcc, v4, v2
	s_nop 1
	v_cndmask_b32_e32 v1, v1, v5, vcc
	v_mul_lo_u32 v4, v2, v1
	v_add_u32_e32 v2, v4, v2
	v_cmp_ne_u32_e32 vcc, v3, v2
	s_and_saveexec_b64 s[0:1], vcc
	s_xor_b64 s[8:9], exec, s[0:1]
	s_cbranch_execz .LBB0_1064
	s_waitcnt lgkmcnt(0)
	global_load_dword v0, v201, s[6:7] offset:1024 sc1
	s_add_u32 s12, s6, 0x2400
	s_addc_u32 s13, s7, 0
	s_waitcnt vmcnt(0)
	v_cmp_eq_u32_e32 vcc, v0, v1
	s_and_saveexec_b64 s[10:11], vcc
	s_cbranch_execz .LBB0_1063
	s_mov_b32 s0, 1
	s_mov_b64 s[14:15], 0
	s_branch .LBB0_1054

; __device__ __forceinline__ unsigned xb_ld(unsigned* p)              { return __hip_atomic_load(p, __ATOMIC_RELAXED, __HIP_MEMORY_SCOPE_AGENT); }
; #define XB_SPIN(cond, bar) do { unsigned _sp = 0; while (cond) { __builtin_amdgcn_s_sleep(1); \
;     if ((++_sp & 255u) == 0u) { if (xb_ld(&(bar)[XB_TMO])) break; if (_sp > XB_SPIN_CAP) { atomicAdd(&(bar)[XB_TMO], 1u); break; } } } } while (0)
; __device__ __forceinline__ void xcd_barrier(const XcdBarrier& b) {
;     ...
;             XB_SPIN(xb_ld(&bar[XB_XGEN(b.x)]) == gen, bar);
;             __builtin_amdgcn_fence(__ATOMIC_ACQUIRE, "agent");
;             asm volatile("s_waitcnt vmcnt(0)" ::: "memory");
.LBB0_1063:
	s_or_b64 exec, exec, s[10:11]
	s_waitcnt vmcnt(0)
	s_waitcnt vmcnt(0)
